# grid barrier: 8 counter shards at 128-B spacing instead of 4 at 256 B
# baseline (speedup 1.0000x reference)
; __global__ __launch_bounds__(NTHR, 1) void hymba_mega(Params P) {
;   extern __shared__ __attribute__((aligned(16))) char lds[];
;   cg::grid_group grid = cg::this_grid();
;   unsigned* bctr = reinterpret_cast<unsigned*>(P.ws + O_CONST + 8192 - 256);
;   if (blockIdx.x == 0 && threadIdx.x == 0) *bctr = 0u;
;   if (blockIdx.x == 0 && threadIdx.x < 64) reinterpret_cast<unsigned*>(P.ws + O_CONST + 8192 - 512)[threadIdx.x] = 0u;
_Z10hymba_mega6Params:
	s_load_dwordx8 s[52:59], s[0:1], 0x80
	s_load_dword s26, s[0:1], 0xa0
	s_mov_b32 s98, s2
	v_and_b32_e32 v226, 0x3ff, v0
	s_add_u32 s2, s0, 0xa0
	v_or_b32_e32 v1, s98, v226
	s_addc_u32 s3, s1, 0
	v_cmp_eq_u32_e32 vcc, 0, v1
	s_and_saveexec_b64 s[4:5], vcc
	s_cbranch_execz .LBB0_2
	v_mov_b32_e32 v1, 0xf7a1000
	v_mov_b32_e32 v2, 0
	s_waitcnt lgkmcnt(0)
	global_store_dword v1, v2, s[58:59] offset:3840
	global_store_dword v1, v2, s[58:59] offset:-1024
	global_store_dword v1, v2, s[58:59] offset:-896
	global_store_dword v1, v2, s[58:59] offset:-768
	global_store_dword v1, v2, s[58:59] offset:-640
	global_store_dword v1, v2, s[58:59] offset:-512
	global_store_dword v1, v2, s[58:59] offset:-384
	global_store_dword v1, v2, s[58:59] offset:-256
	global_store_dword v1, v2, s[58:59] offset:-128

; DEV void grid_bar(unsigned* ctr, unsigned target) {
;   asm volatile("s_waitcnt vmcnt(0)" ::: "memory");
;   __syncthreads();
;   if (threadIdx.x == 0) {
;     __builtin_amdgcn_fence(__ATOMIC_RELEASE, "agent");
;     asm volatile("s_waitcnt vmcnt(0)" ::: "memory");
;     __hip_atomic_fetch_add(ctr, 1u, __ATOMIC_RELAXED, __HIP_MEMORY_SCOPE_AGENT);
;     while (__hip_atomic_load(ctr, __ATOMIC_RELAXED, __HIP_MEMORY_SCOPE_AGENT) < target) __builtin_amdgcn_s_sleep(1);
;     __builtin_amdgcn_fence(__ATOMIC_ACQUIRE, "agent");
;     asm volatile("s_waitcnt vmcnt(0)" ::: "memory");
;   }
;   __syncthreads();
; }
.LBB0_348:
	s_waitcnt vmcnt(0)
	s_waitcnt vmcnt(0) lgkmcnt(0)
	s_barrier
	s_and_saveexec_b64 s[2:3], s[0:1]
	s_cbranch_execz .LBB0_353
	v_mov_b32_e32 v0, s86
	v_add_co_u32_e32 v0, vcc, 0xf7a1000, v0
	v_mov_b32_e32 v1, s87
	buffer_wbl2 sc1
	s_waitcnt vmcnt(0)
	v_addc_co_u32_e32 v1, vcc, 0, v1, vcc
	v_readlane_b32 s12, v254, 26
	v_readlane_b32 s4, v254, 40
	s_add_i32 s10, s4, 1
	s_add_u32 s4, s86, 0xf7a1f00
	s_mul_i32 s10, s10, s94
	s_addc_u32 s5, s87, 0
	s_and_b32 s12, s12, 7
	s_lshl_b32 s12, s12, 7
	s_sub_u32 s4, s4, 0x1300
	s_subb_u32 s5, s5, 0
	s_add_u32 s12, s4, s12
	s_addc_u32 s13, s5, 0
	v_mov_b32_e32 v0, s12
	v_mov_b32_e32 v1, s13
	flat_atomic_add v[0:1], v228
	s_mov_b32 s11, 0
.Lgb_loop_0:
	v_mov_b64_e32 v[0:1], s[4:5]
	flat_load_dword v240, v[0:1] sc1
	flat_load_dword v241, v[0:1] offset:128 sc1
	flat_load_dword v242, v[0:1] offset:256 sc1
	flat_load_dword v243, v[0:1] offset:384 sc1
	flat_load_dword v244, v[0:1] offset:512 sc1
	flat_load_dword v245, v[0:1] offset:640 sc1
	flat_load_dword v246, v[0:1] offset:768 sc1
	flat_load_dword v247, v[0:1] offset:896 sc1
	s_waitcnt vmcnt(0) lgkmcnt(0)
	v_add3_u32 v240, v240, v241, v242
	v_add3_u32 v240, v240, v243, v244
	v_add3_u32 v240, v240, v245, v246
	v_add_u32_e32 v240, v240, v247
	s_nop 0
	v_readfirstlane_b32 s12, v240
	s_cmp_ge_u32 s12, s10
	s_cbranch_scc1 .Lgb_done_0
	s_sleep 6
	s_add_u32 s11, s11, 1
	s_cmp_lt_u32 s11, 0x20000
	s_cbranch_scc1 .Lgb_loop_0

; DEV void grid_bar(unsigned* ctr, unsigned target) {
;   asm volatile("s_waitcnt vmcnt(0)" ::: "memory");
;   __syncthreads();
;   if (threadIdx.x == 0) {
;     __builtin_amdgcn_fence(__ATOMIC_RELEASE, "agent");
;     asm volatile("s_waitcnt vmcnt(0)" ::: "memory");
;     __hip_atomic_fetch_add(ctr, 1u, __ATOMIC_RELAXED, __HIP_MEMORY_SCOPE_AGENT);
;     while (__hip_atomic_load(ctr, __ATOMIC_RELAXED, __HIP_MEMORY_SCOPE_AGENT) < target) __builtin_amdgcn_s_sleep(1);
;     __builtin_amdgcn_fence(__ATOMIC_ACQUIRE, "agent");
;     asm volatile("s_waitcnt vmcnt(0)" ::: "memory");
;   }
;   __syncthreads();
; }
.LBB0_360:
	s_waitcnt vmcnt(0)
	s_barrier
	s_and_saveexec_b64 s[2:3], s[0:1]
	s_cbranch_execz .LBB0_365
	v_mov_b32_e32 v0, s4
	v_add_co_u32_e32 v0, vcc, 0xf7a1000, v0
	v_mov_b32_e32 v1, s5
	buffer_wbl2 sc1
	s_waitcnt vmcnt(0)
	s_waitcnt vmcnt(0)
	v_addc_co_u32_e32 v1, vcc, 0, v1, vcc
	v_readlane_b32 s12, v254, 26
	v_readlane_b32 s6, v254, 40
	s_add_i32 s10, s6, 2
	s_add_u32 s4, s4, 0xf7a1f00
	s_mul_i32 s10, s10, s94
	s_addc_u32 s5, s5, 0
	s_and_b32 s12, s12, 7
	s_lshl_b32 s12, s12, 7
	s_sub_u32 s4, s4, 0x1300
	s_subb_u32 s5, s5, 0
	s_add_u32 s12, s4, s12
	s_addc_u32 s13, s5, 0
	v_mov_b32_e32 v0, s12
	v_mov_b32_e32 v1, s13
	flat_atomic_add v[0:1], v228
	s_mov_b32 s11, 0

; DEV void grid_bar(unsigned* ctr, unsigned target) {
;   asm volatile("s_waitcnt vmcnt(0)" ::: "memory");
;   __syncthreads();
;   if (threadIdx.x == 0) {
;     __builtin_amdgcn_fence(__ATOMIC_RELEASE, "agent");
;     asm volatile("s_waitcnt vmcnt(0)" ::: "memory");
;     __hip_atomic_fetch_add(ctr, 1u, __ATOMIC_RELAXED, __HIP_MEMORY_SCOPE_AGENT);
;     while (__hip_atomic_load(ctr, __ATOMIC_RELAXED, __HIP_MEMORY_SCOPE_AGENT) < target) __builtin_amdgcn_s_sleep(1);
;     __builtin_amdgcn_fence(__ATOMIC_ACQUIRE, "agent");
;     asm volatile("s_waitcnt vmcnt(0)" ::: "memory");
;   }
;   __syncthreads();
; }
.LBB0_399:
	s_waitcnt vmcnt(0)
	v_readlane_b32 s2, v254, 40
	s_add_i32 s34, s2, 3
	s_barrier
	s_and_saveexec_b64 s[2:3], s[0:1]
	s_cbranch_execz .LBB0_404
	v_mov_b32_e32 v0, s4
	v_add_co_u32_e32 v0, vcc, 0xf7a1000, v0
	v_mov_b32_e32 v1, s5
	buffer_wbl2 sc1
	s_waitcnt vmcnt(0)
	s_waitcnt vmcnt(0)
	v_addc_co_u32_e32 v1, vcc, 0, v1, vcc
	v_readlane_b32 s12, v254, 26
	s_add_u32 s4, s4, 0xf7a1f00
	s_mul_i32 s10, s34, s94
	s_addc_u32 s5, s5, 0
	s_and_b32 s12, s12, 7
	s_lshl_b32 s12, s12, 7
	s_sub_u32 s4, s4, 0x1300
	s_subb_u32 s5, s5, 0
	s_add_u32 s12, s4, s12
	s_addc_u32 s13, s5, 0
	v_mov_b32_e32 v0, s12
	v_mov_b32_e32 v1, s13
	flat_atomic_add v[0:1], v228
	s_mov_b32 s11, 0

; DEV void grid_bar(unsigned* ctr, unsigned target) {
;   asm volatile("s_waitcnt vmcnt(0)" ::: "memory");
;   __syncthreads();
;   if (threadIdx.x == 0) {
;     __builtin_amdgcn_fence(__ATOMIC_RELEASE, "agent");
;     asm volatile("s_waitcnt vmcnt(0)" ::: "memory");
;     __hip_atomic_fetch_add(ctr, 1u, __ATOMIC_RELAXED, __HIP_MEMORY_SCOPE_AGENT);
;     while (__hip_atomic_load(ctr, __ATOMIC_RELAXED, __HIP_MEMORY_SCOPE_AGENT) < target) __builtin_amdgcn_s_sleep(1);
;     __builtin_amdgcn_fence(__ATOMIC_ACQUIRE, "agent");
;     asm volatile("s_waitcnt vmcnt(0)" ::: "memory");
;   }
;   __syncthreads();
; }
.LBB0_474:
	v_readlane_b32 s2, v254, 41
	v_readlane_b32 s3, v254, 42
	s_and_b64 s[2:3], s[96:97], s[2:3]
	s_and_b64 vcc, exec, s[2:3]
	s_cbranch_vccnz .LBB0_481
	s_waitcnt vmcnt(0)
	v_readlane_b32 s2, v254, 40
	s_add_i32 s34, s2, 4
	s_waitcnt lgkmcnt(0)
	s_barrier
	s_and_saveexec_b64 s[2:3], s[0:1]
	s_cbranch_execz .LBB0_480
	v_mov_b32_e32 v0, s10
	v_add_co_u32_e32 v0, vcc, 0xf7a1000, v0
	v_mov_b32_e32 v1, s11
	buffer_wbl2 sc1
	s_waitcnt vmcnt(0)
	s_waitcnt vmcnt(0)
	v_addc_co_u32_e32 v1, vcc, 0, v1, vcc
	v_readlane_b32 s12, v254, 26
	s_add_u32 s4, s10, 0xf7a1f00
	s_mul_i32 s10, s34, s94
	s_addc_u32 s5, s11, 0
	s_and_b32 s12, s12, 7
	s_lshl_b32 s12, s12, 7
	s_sub_u32 s4, s4, 0x1300
	s_subb_u32 s5, s5, 0
	s_add_u32 s12, s4, s12
	s_addc_u32 s13, s5, 0
	v_mov_b32_e32 v0, s12
	v_mov_b32_e32 v1, s13
	flat_atomic_add v[0:1], v228
	s_mov_b32 s11, 0
